# side waves of the chunk-scan phase pace their w_in conversion (s_sleep per item): less memory contention for the scan's critical path
# speedup vs baseline: 1.0091x; 1.0091x over previous
.LBB0_1072:
	s_sleep 127
	s_mul_hi_i32 s2, s7, 0x88888889
	s_add_i32 s2, s2, s7
	s_lshr_b32 s3, s2, 31
	s_ashr_i32 s2, s2, 7
	s_add_i32 s8, s2, s3
	s_lshl_b32 s2, s8, 5
	s_mul_i32 s3, s8, 0xffffc400
	v_add_u32_e32 v4, s3, v0
	s_ashr_i32 s3, s2, 31
	s_mul_i32 s8, s8, 0x1e0000
	s_mul_hi_i32 s9, s2, 0xf000
	s_add_u32 s8, s4, s8
	s_addc_u32 s9, s5, s9
	v_ashrrev_i32_e32 v5, 31, v4
	v_lshl_add_u64 v[6:7], v[4:5], 2, s[8:9]
	s_mov_b32 s8, 0xf000
	v_add_co_u32_e32 v8, vcc, s8, v6
	s_mov_b32 s8, 0x2d000
	s_nop 0
	v_addc_co_u32_e32 v9, vcc, 0, v7, vcc
	v_add_co_u32_e32 v10, vcc, s95, v6
	global_load_dword v3, v[6:7], off nt
	s_nop 0
	v_addc_co_u32_e32 v11, vcc, 0, v7, vcc
	global_load_dword v8, v[8:9], off nt
	v_lshlrev_b64 v[4:5], 12, v[4:5]
	global_load_dword v9, v[10:11], off nt
	v_add_co_u32_e32 v10, vcc, s8, v6
	s_mov_b32 s8, 0x4b000
	s_nop 0
	v_addc_co_u32_e32 v11, vcc, 0, v7, vcc
	v_add_co_u32_e32 v12, vcc, s87, v6
	global_load_dword v10, v[10:11], off nt
	s_nop 0
	v_addc_co_u32_e32 v13, vcc, 0, v7, vcc
	global_load_dword v11, v[12:13], off nt
	v_add_co_u32_e32 v12, vcc, s8, v6
	s_mov_b32 s8, 0x5a000
	s_nop 0
	v_addc_co_u32_e32 v13, vcc, 0, v7, vcc
	v_add_co_u32_e32 v14, vcc, s8, v6
	s_mov_b32 s8, 0x69000
	s_nop 0
	v_addc_co_u32_e32 v15, vcc, 0, v7, vcc
	global_load_dword v12, v[12:13], off nt
	v_lshl_add_u64 v[4:5], s[0:1], 0, v[4:5]
	global_load_dword v13, v[14:15], off nt
	v_add_co_u32_e32 v14, vcc, s8, v6
	s_mov_b32 s8, 0x87000
	s_nop 0
	v_addc_co_u32_e32 v15, vcc, 0, v7, vcc
	v_add_co_u32_e32 v16, vcc, s12, v6
	global_load_dword v14, v[14:15], off nt
	s_nop 0
	v_addc_co_u32_e32 v17, vcc, 0, v7, vcc
	global_load_dword v15, v[16:17], off nt
	v_add_co_u32_e32 v16, vcc, s8, v6
	s_mov_b32 s8, 0x96000
	s_nop 0
	v_addc_co_u32_e32 v17, vcc, 0, v7, vcc
	v_add_co_u32_e32 v18, vcc, s8, v6
	s_mov_b32 s8, 0xa5000
	s_nop 0
	v_addc_co_u32_e32 v19, vcc, 0, v7, vcc
	global_load_dword v16, v[16:17], off nt
	s_add_i32 s7, s7, s37
	global_load_dword v17, v[18:19], off nt
	v_add_co_u32_e32 v18, vcc, s8, v6
	s_mov_b32 s8, 0xb4000
	s_nop 0
	v_addc_co_u32_e32 v19, vcc, 0, v7, vcc
	global_load_dword v20, v[18:19], off nt
	v_add_co_u32_e32 v18, vcc, s8, v6
	s_mov_b32 s8, 0xc3000
	s_nop 0
	v_addc_co_u32_e32 v19, vcc, 0, v7, vcc
	global_load_dword v21, v[18:19], off nt
	v_add_co_u32_e32 v18, vcc, s8, v6
	s_mov_b32 s8, 0xd2000
	s_nop 0
	v_addc_co_u32_e32 v19, vcc, 0, v7, vcc
	global_load_dword v22, v[18:19], off nt
	v_add_co_u32_e32 v18, vcc, s8, v6
	s_mov_b32 s8, 0xe1000
	s_nop 0
	v_addc_co_u32_e32 v19, vcc, 0, v7, vcc
	global_load_dword v23, v[18:19], off nt
	v_add_co_u32_e32 v18, vcc, s8, v6
	s_mov_b32 s8, 0xff000
	s_nop 0
	v_addc_co_u32_e32 v19, vcc, 0, v7, vcc
	global_load_dword v24, v[18:19], off nt
	v_add_co_u32_e32 v18, vcc, s13, v6
	v_add_u32_e32 v0, s6, v0
	s_nop 0
	v_addc_co_u32_e32 v19, vcc, 0, v7, vcc
	global_load_dword v25, v[18:19], off nt
	v_add_co_u32_e32 v18, vcc, s8, v6
	s_mov_b32 s8, 0x10e000
	s_nop 0
	v_addc_co_u32_e32 v19, vcc, 0, v7, vcc
	global_load_dword v26, v[18:19], off nt
	v_add_co_u32_e32 v18, vcc, s8, v6
	s_mov_b32 s8, 0x11d000
	s_nop 0
	v_addc_co_u32_e32 v19, vcc, 0, v7, vcc
	global_load_dword v27, v[18:19], off nt
	v_add_co_u32_e32 v18, vcc, s8, v6
	s_mov_b32 s8, 0x12c000
	s_nop 0
	v_addc_co_u32_e32 v19, vcc, 0, v7, vcc
	global_load_dword v28, v[18:19], off nt
	v_add_co_u32_e32 v18, vcc, s8, v6
	s_mov_b32 s8, 0x13b000
	s_nop 0
	v_addc_co_u32_e32 v19, vcc, 0, v7, vcc
	global_load_dword v29, v[18:19], off nt
	v_add_co_u32_e32 v18, vcc, s8, v6
	s_mov_b32 s8, 0x14a000
	s_nop 0
	v_addc_co_u32_e32 v19, vcc, 0, v7, vcc
	global_load_dword v30, v[18:19], off nt
	v_add_co_u32_e32 v18, vcc, s8, v6
	s_mov_b32 s8, 0x159000
	s_nop 0
	v_addc_co_u32_e32 v19, vcc, 0, v7, vcc
	global_load_dword v31, v[18:19], off nt
	v_add_co_u32_e32 v18, vcc, s8, v6
	s_mov_b32 s8, 0x168000
	s_nop 0
	v_addc_co_u32_e32 v19, vcc, 0, v7, vcc
	global_load_dword v32, v[18:19], off nt
	v_add_co_u32_e32 v18, vcc, s8, v6
	s_mov_b32 s8, 0x177000
	s_nop 0
	v_addc_co_u32_e32 v19, vcc, 0, v7, vcc
	global_load_dword v33, v[18:19], off nt
	v_add_co_u32_e32 v18, vcc, s8, v6
	s_mov_b32 s8, 0x186000
	s_nop 0
	v_addc_co_u32_e32 v19, vcc, 0, v7, vcc
	global_load_dword v34, v[18:19], off nt
	v_add_co_u32_e32 v18, vcc, s8, v6
	s_mov_b32 s8, 0x195000
	s_nop 0
	v_addc_co_u32_e32 v19, vcc, 0, v7, vcc
	global_load_dword v35, v[18:19], off nt
	v_add_co_u32_e32 v18, vcc, s8, v6
	s_mov_b32 s8, 0x1a4000
	s_nop 0
	v_addc_co_u32_e32 v19, vcc, 0, v7, vcc
	global_load_dword v36, v[18:19], off nt
	v_add_co_u32_e32 v18, vcc, s8, v6
	s_mov_b32 s8, 0x1b3000
	s_nop 0
	v_addc_co_u32_e32 v19, vcc, 0, v7, vcc
	global_load_dword v37, v[18:19], off nt
	v_add_co_u32_e32 v18, vcc, s8, v6
	s_mov_b32 s8, 0x1c2000
	s_nop 0
	v_addc_co_u32_e32 v19, vcc, 0, v7, vcc
	global_load_dword v38, v[18:19], off nt
	v_add_co_u32_e32 v18, vcc, s8, v6
	s_mov_b32 s8, 0x1d1000
	s_nop 0
	v_addc_co_u32_e32 v19, vcc, 0, v7, vcc
	v_add_co_u32_e32 v6, vcc, s8, v6
	global_load_dword v39, v[18:19], off nt
	s_nop 0
	v_addc_co_u32_e32 v7, vcc, 0, v7, vcc
	global_load_dword v40, v[6:7], off nt
	v_lshl_add_u64 v[18:19], s[2:3], 1, v[4:5]
	s_waitcnt vmcnt(0)
	v_cvt_pk_bf16_f32 v4, v3, v8
	v_cvt_pk_bf16_f32 v5, v9, v10
	v_cvt_pk_bf16_f32 v6, v11, v12
	v_cvt_pk_bf16_f32 v7, v13, v14
	global_store_dwordx4 v[18:19], v[4:7], off
	s_cmpk_gt_i32 s7, 0x3bff
	s_nop 0
	v_cvt_pk_bf16_f32 v4, v15, v16
	v_cvt_pk_bf16_f32 v5, v17, v20
	v_cvt_pk_bf16_f32 v6, v21, v22
	v_cvt_pk_bf16_f32 v7, v23, v24
	global_store_dwordx4 v[18:19], v[4:7], off offset:16
	s_nop 1
	v_cvt_pk_bf16_f32 v4, v25, v26
	v_cvt_pk_bf16_f32 v5, v27, v28
	v_cvt_pk_bf16_f32 v6, v29, v30
	v_cvt_pk_bf16_f32 v7, v31, v32
	global_store_dwordx4 v[18:19], v[4:7], off offset:32
	s_nop 1
	v_cvt_pk_bf16_f32 v4, v33, v34
	v_cvt_pk_bf16_f32 v5, v35, v36
	v_cvt_pk_bf16_f32 v6, v37, v38
	v_cvt_pk_bf16_f32 v7, v39, v40
	global_store_dwordx4 v[18:19], v[4:7], off offset:48
	s_cbranch_scc0 .LBB0_1072
